# v3 + NA items offloaded to idle sample-scan workgroups + NA next-head K/V prefetch no longer drained before the S MFMAs + static priority for waves 4-7 (hipcc flips removed) + nt hint on residual-stre
# speedup vs baseline: 1.0033x; 1.0033x over previous
; #define LAS __attribute__((address_space(3)))
; __device__ __forceinline__ void na_item(const Args& a, int layer, int item, LAS unsigned char* lds, int tid, int lane, int wave) {
;     ...
;         __syncthreads();
;         if (h + 1 < 8) {
; #pragma unroll
;             for (int it = 0; it < 8; ++it) { kreg[it] = *(const u32x4*)(KNA + kvoff + (size_t)it * (64 * 512) + (h + 1) * 64); vreg[it] = *(const u32x4*)(VNA + kvoff + (size_t)it * (64 * 512) + (h + 1) * 64); }
;         }
;         f32x16 acc[2][2];
; #pragma unroll
;         for (int mt = 0; mt < 2; ++mt)
; #pragma unroll
;             for (int nt = 0; nt < 2; ++nt)
; #pragma unroll
;                 for (int r = 0; r < 16; ++r) acc[mt][nt][r] = 0.f;
; #pragma unroll
;         for (int mt = 0; mt < 2; ++mt)
; #pragma unroll
;             for (int ks = 0; ks < 4; ++ks) {
;                 const h16x8 kf = *(const LAS h16x8*)(lds + (aw * 64 + 32 * mt + l31) * NA_PITCH + (16 * ks + 8 * half) * 2);
;                 acc[mt][0] = __builtin_amdgcn_mfma_f32_32x32x16_f16(kf, qf[0][ks], acc[mt][0], 0, 0, 0);
;                 acc[mt][1] = __builtin_amdgcn_mfma_f32_32x32x16_f16(kf, qf[1][ks], acc[mt][1], 0, 0, 0);
;             }
;         float mxq[2], lq[2];
; #pragma unroll
;         for (int nt = 0; nt < 2; ++nt) {
;             const int qc = l31 + 32 * nt; int csq = qc - 8; csq = csq < 0 ? 0 : (csq > 48 ? 48 : csq);
;             const int dlt = 4 * half - csq;
;             const LAS float* bq = bt + (48 + 15 + 4 * half - qc - 32);
;             float m = -3.0e38f;
; #pragma unroll
;             for (int mt = 0; mt < 2; ++mt)
; #pragma unroll
;                 for (int r = 0; r < 16; ++r) { const int kr = (r & 3) + 8 * (r >> 2) + 32 * mt;
;                     const float sv = acc[mt][nt][r] + bq[32 + kr]; const bool ok = (unsigned)(dlt + kr) < 16u; const float sm = ok ? sv : -1.0e30f; acc[mt][nt][r] = sm; m = fmaxf(m, sm); }
;             { const auto sw = __builtin_amdgcn_permlane32_swap(__builtin_bit_cast(unsigned, m), __builtin_bit_cast(unsigned, m), false, false); const unsigned s0 = sw[0], s1 = sw[1]; m = fmaxf(__builtin_bit_cast(float, s0), __builtin_bit_cast(float, s1)); }
.LBB0_459:
	s_or_b64 exec, exec, s[2:3]
	s_cmpk_eq_i32 s4, 0x380
	s_waitcnt vmcnt(0) lgkmcnt(0)
	s_barrier
	s_cbranch_scc1 .LBB0_461
	v_lshl_add_u64 v[8:9], v[178:179], 0, s[4:5]
	v_add_co_u32_e32 v12, vcc, 0x10000, v8
	v_lshl_add_u64 v[10:11], v[180:181], 0, s[4:5]
	s_nop 0
	v_addc_co_u32_e32 v13, vcc, 0, v9, vcc
	v_add_co_u32_e32 v14, vcc, 0x10000, v10
	global_load_dwordx4 v[64:67], v[8:9], off offset:128
	global_load_dwordx4 v[68:71], v[10:11], off offset:128
	v_addc_co_u32_e32 v15, vcc, 0, v11, vcc
	global_load_dwordx4 v[72:75], v[12:13], off offset:128
	global_load_dwordx4 v[76:79], v[14:15], off offset:128
	v_add_co_u32_e32 v12, vcc, 0x20000, v8
	s_nop 1
	v_addc_co_u32_e32 v13, vcc, 0, v9, vcc
	v_add_co_u32_e32 v14, vcc, 0x20000, v10
	s_nop 1
	v_addc_co_u32_e32 v15, vcc, 0, v11, vcc
	global_load_dwordx4 v[80:83], v[12:13], off offset:128
	global_load_dwordx4 v[84:87], v[14:15], off offset:128
	v_add_co_u32_e32 v12, vcc, 0x30000, v8
	s_nop 1
	v_addc_co_u32_e32 v13, vcc, 0, v9, vcc
	v_add_co_u32_e32 v14, vcc, 0x30000, v10
	s_nop 1
	v_addc_co_u32_e32 v15, vcc, 0, v11, vcc
	global_load_dwordx4 v[88:91], v[12:13], off offset:128
	global_load_dwordx4 v[92:95], v[14:15], off offset:128
	v_add_co_u32_e32 v12, vcc, 0x40000, v8
	s_nop 1
	v_addc_co_u32_e32 v13, vcc, 0, v9, vcc
	v_add_co_u32_e32 v14, vcc, 0x40000, v10
	s_nop 1
	v_addc_co_u32_e32 v15, vcc, 0, v11, vcc
	global_load_dwordx4 v[96:99], v[12:13], off offset:128
	global_load_dwordx4 v[100:103], v[14:15], off offset:128
	v_add_co_u32_e32 v12, vcc, 0x50000, v8
	s_nop 1
	v_addc_co_u32_e32 v13, vcc, 0, v9, vcc
	v_add_co_u32_e32 v14, vcc, 0x50000, v10
	s_nop 1
	v_addc_co_u32_e32 v15, vcc, 0, v11, vcc
	global_load_dwordx4 v[104:107], v[12:13], off offset:128
	global_load_dwordx4 v[108:111], v[14:15], off offset:128
	v_add_co_u32_e32 v12, vcc, 0x60000, v8
	s_nop 1
	v_addc_co_u32_e32 v13, vcc, 0, v9, vcc
	v_add_co_u32_e32 v14, vcc, 0x60000, v10
	s_nop 1
	v_addc_co_u32_e32 v15, vcc, 0, v11, vcc
	v_add_co_u32_e32 v8, vcc, 0x70000, v8
	global_load_dwordx4 v[112:115], v[12:13], off offset:128
	global_load_dwordx4 v[116:119], v[14:15], off offset:128
	v_addc_co_u32_e32 v9, vcc, 0, v9, vcc
	v_add_co_u32_e32 v10, vcc, 0x70000, v10
	s_nop 1
	v_addc_co_u32_e32 v11, vcc, 0, v11, vcc
	global_load_dwordx4 v[120:123], v[8:9], off offset:128
	global_load_dwordx4 v[124:127], v[10:11], off offset:128
.LBB0_461:
	ds_read_b128 v[8:11], v219
	ds_read_b128 v[40:43], v219 offset:32
	v_readlane_b32 s2, v254, 55
	v_readlane_b32 s3, v254, 56
	s_waitcnt lgkmcnt(1)
	v_mfma_f32_32x32x16_f16 v[24:39], v[8:11], v[0:3], 0
	ds_read_b128 v[144:147], v219 offset:4640
	v_mfma_f32_32x32x16_f16 v[8:23], v[8:11], v[4:7], 0
	s_waitcnt lgkmcnt(1)
	v_mfma_f32_32x32x16_f16 v[24:39], v[40:43], v[136:139], v[24:39]
	v_mfma_f32_32x32x16_f16 v[8:23], v[40:43], v[140:143], v[8:23]
	ds_read_b128 v[40:43], v219 offset:64
	s_waitcnt lgkmcnt(0)
	v_mfma_f32_32x32x16_f16 v[24:39], v[40:43], v[128:131], v[24:39]
	v_mfma_f32_32x32x16_f16 v[8:23], v[40:43], v[132:135], v[8:23]
	ds_read_b128 v[40:43], v219 offset:96
	s_waitcnt lgkmcnt(0)
	v_mfma_f32_32x32x16_f16 v[8:23], v[40:43], v[60:63], v[8:23]
	v_mfma_f32_32x32x16_f16 v[24:39], v[40:43], v[56:59], v[24:39]
	s_nop 10
	ds_read_b128 v[8:11], v219 offset:4608
	s_waitcnt lgkmcnt(0)
	v_mfma_f32_32x32x16_f16 v[40:55], v[8:11], v[0:3], 0
	v_mfma_f32_32x32x16_f16 v[40:55], v[144:147], v[136:139], v[40:55]
	ds_read_b128 v[136:139], v219 offset:4672
	s_waitcnt lgkmcnt(0)
	v_mfma_f32_32x32x16_f16 v[40:55], v[136:139], v[128:131], v[40:55]
	ds_read_b128 v[128:131], v219 offset:4704
	s_waitcnt lgkmcnt(0)
	v_mfma_f32_32x32x16_f16 v[40:55], v[128:131], v[56:59], v[40:55]
	v_mfma_f32_32x32x16_f16 v[0:15], v[8:11], v[4:7], 0
	s_nop 10
	ds_read2_b32 v[44:45], v196 offset0:63 offset1:64
	s_waitcnt lgkmcnt(0)
	v_add_f32_e32 v16, v24, v44
	v_add_f32_e32 v24, v25, v45
	v_cndmask_b32_e64 v45, v209, v24, s[20:21]
	ds_read2_b32 v[24:25], v196 offset0:65 offset1:66
	v_cndmask_b32_e64 v16, v209, v16, s[2:3]
	v_max_f32_e32 v44, 0xff61b1e6, v16
	s_mov_b32 s2, 0xf149f2ca
	v_mfma_f32_32x32x16_f16 v[0:15], v[144:147], v[140:143], v[0:15]
	s_waitcnt lgkmcnt(0)
	v_add_f32_e32 v24, v26, v24
	v_cndmask_b32_e64 v26, v209, v24, s[24:25]
	v_add_f32_e32 v24, v27, v25
	v_cndmask_b32_e64 v27, v209, v24, s[44:45]
	ds_read2_b32 v[24:25], v196 offset0:71 offset1:72
	v_max3_f32 v44, v44, v45, v26
	s_waitcnt lgkmcnt(0)
	v_add_f32_e32 v24, v28, v24
	v_cndmask_b32_e64 v28, v209, v24, s[28:29]
	v_add_f32_e32 v24, v29, v25
	v_cndmask_b32_e64 v29, v209, v24, s[22:23]
	ds_read2_b32 v[24:25], v196 offset0:73 offset1:74
	v_max3_f32 v44, v44, v27, v28
	v_mfma_f32_32x32x16_f16 v[0:15], v[136:139], v[132:135], v[0:15]
	s_waitcnt lgkmcnt(0)
	v_add_f32_e32 v24, v30, v24
	v_cndmask_b32_e64 v30, v209, v24, s[34:35]
	v_add_f32_e32 v24, v31, v25
	v_cndmask_b32_e64 v31, v209, v24, s[54:55]
	ds_read2_b32 v[24:25], v196 offset0:79 offset1:80
	v_max3_f32 v44, v44, v29, v30
	v_mfma_f32_32x32x16_f16 v[0:15], v[128:131], v[60:63], v[0:15]
	s_waitcnt lgkmcnt(0)
	v_add_f32_e32 v24, v32, v24
	v_cndmask_b32_e64 v32, v209, v24, s[58:59]
	v_add_f32_e32 v24, v33, v25
	v_cndmask_b32_e64 v33, v209, v24, s[62:63]
	ds_read2_b32 v[24:25], v196 offset0:81 offset1:82
	v_max3_f32 v44, v44, v31, v32
	s_waitcnt lgkmcnt(0)
	v_add_f32_e32 v24, v34, v24
	v_cndmask_b32_e64 v34, v209, v24, s[52:53]
	v_add_f32_e32 v24, v35, v25
	v_cndmask_b32_e64 v35, v209, v24, s[56:57]
	ds_read2_b32 v[24:25], v196 offset0:87 offset1:88
	v_max3_f32 v44, v44, v33, v34
	s_waitcnt lgkmcnt(0)
; #define LAS __attribute__((address_space(3)))
; __device__ __forceinline__ void na_item(const Args& a, int layer, int item, LAS unsigned char* lds, int tid, int lane, int wave) {
;     ...
;         float mxq[2], lq[2];
; #pragma unroll
;         for (int nt = 0; nt < 2; ++nt) {
;             const int qc = l31 + 32 * nt; int csq = qc - 8; csq = csq < 0 ? 0 : (csq > 48 ? 48 : csq);
;             const int dlt = 4 * half - csq;
;             const LAS float* bq = bt + (48 + 15 + 4 * half - qc - 32);
;             float m = -3.0e38f;
; #pragma unroll
;             for (int mt = 0; mt < 2; ++mt)
; #pragma unroll
;                 for (int r = 0; r < 16; ++r) { const int kr = (r & 3) + 8 * (r >> 2) + 32 * mt;
;                     const float sv = acc[mt][nt][r] + bq[32 + kr]; const bool ok = (unsigned)(dlt + kr) < 16u; const float sm = ok ? sv : -1.0e30f; acc[mt][nt][r] = sm; m = fmaxf(m, sm); }
;             { const auto sw = __builtin_amdgcn_permlane32_swap(__builtin_bit_cast(unsigned, m), __builtin_bit_cast(unsigned, m), false, false); const unsigned s0 = sw[0], s1 = sw[1]; m = fmaxf(__builtin_bit_cast(float, s0), __builtin_bit_cast(float, s1)); }
;             float l = 0.f;
; #pragma unroll
;             for (int mt = 0; mt < 2; ++mt)
; #pragma unroll
;                 for (int r = 0; r < 16; ++r) { const float p = __expf(acc[mt][nt][r] - m); acc[mt][nt][r] = p; l += p; }
;             { const auto sw = __builtin_amdgcn_permlane32_swap(__builtin_bit_cast(unsigned, l), __builtin_bit_cast(unsigned, l), false, false); const unsigned s0 = sw[0], s1 = sw[1]; l = __builtin_bit_cast(float, s0) + __builtin_bit_cast(float, s1); }
;             mxq[nt] = m; lq[nt] = l;
;         }
;         h16x8 pf[2][2][2];
; #pragma unroll
;         for (int kt = 0; kt < 2; ++kt)
; #pragma unroll
;             for (int nt = 0; nt < 2; ++nt)
; #pragma unroll
;                 for (int sx = 0; sx < 2; ++sx)
; #pragma unroll
;                     for (int e = 0; e < 8; ++e) pf[kt][nt][sx][e] = (h16)acc[kt][nt][8 * sx + e];
	v_add_f32_e32 v24, v36, v24
	v_cndmask_b32_e64 v46, v209, v24, s[60:61]
	v_add_f32_e32 v24, v37, v25
	v_max3_f32 v36, v44, v35, v46
	v_cndmask_b32_e64 v44, v209, v24, s[64:65]
	ds_read2_b32 v[24:25], v196 offset0:89 offset1:90
	s_waitcnt lgkmcnt(0)
	v_add_f32_e32 v24, v38, v24
	v_cndmask_b32_e64 v47, v209, v24, s[66:67]
	v_add_f32_e32 v24, v39, v25
	v_cndmask_b32_e64 v48, v209, v24, s[68:69]
	ds_read2_b32 v[24:25], v196 offset0:95 offset1:96
	v_max3_f32 v36, v36, v44, v47
	s_waitcnt lgkmcnt(0)
	v_add_f32_e32 v24, v40, v24
	v_cndmask_b32_e64 v49, v209, v24, s[70:71]
	v_add_f32_e32 v24, v41, v25
	v_cndmask_b32_e64 v50, v209, v24, s[72:73]
	ds_read2_b32 v[24:25], v196 offset0:97 offset1:98
	v_max3_f32 v36, v36, v48, v49
	s_waitcnt lgkmcnt(0)
	v_add_f32_e32 v24, v42, v24
	v_cndmask_b32_e64 v51, v209, v24, s[74:75]
	v_add_f32_e32 v25, v43, v25
	v_max3_f32 v24, v36, v50, v51
	v_cndmask_b32_e64 v52, v209, v25, s[76:77]
	v_max3_f32 v24, v24, v52, s2
	v_mov_b32_e32 v25, v24
	s_nop 1
	v_permlane32_swap_b32_e32 v24, v25
	v_max_f32_e32 v25, v25, v25
	v_max_f32_e32 v24, v24, v24
	v_max_f32_e32 v224, v24, v25
	v_sub_f32_e32 v16, v16, v224
	v_mul_f32_e32 v16, 0x3fb8aa3b, v16
	v_sub_f32_e32 v24, v45, v224
	v_exp_f32_e32 v16, v16
	v_mul_f32_e32 v24, 0x3fb8aa3b, v24
	v_exp_f32_e32 v24, v24
	v_sub_f32_e32 v31, v31, v224
	v_add_f32_e32 v25, 0, v16
	v_mul_f32_e32 v31, 0x3fb8aa3b, v31
	v_add_f32_e32 v36, v24, v25
	v_sub_f32_e32 v25, v26, v224
	v_mul_f32_e32 v25, 0x3fb8aa3b, v25
	v_sub_f32_e32 v26, v27, v224
	v_exp_f32_e32 v25, v25
	v_mul_f32_e32 v26, 0x3fb8aa3b, v26
	v_sub_f32_e32 v27, v28, v224
	v_exp_f32_e32 v26, v26
	v_mul_f32_e32 v27, 0x3fb8aa3b, v27
	v_sub_f32_e32 v28, v29, v224
	v_exp_f32_e32 v27, v27
	v_mul_f32_e32 v28, 0x3fb8aa3b, v28
	v_sub_f32_e32 v29, v30, v224
	v_exp_f32_e32 v28, v28
	v_mul_f32_e32 v29, 0x3fb8aa3b, v29
	v_add_f32_e32 v36, v25, v36
	v_exp_f32_e32 v29, v29
	v_add_f32_e32 v36, v26, v36
	v_exp_f32_e32 v31, v31
	v_add_f32_e32 v36, v27, v36
	v_add_f32_e32 v36, v28, v36
	v_add_f32_e32 v30, v29, v36
	v_add_f32_e32 v36, v31, v30
	v_sub_f32_e32 v30, v32, v224
	v_mul_f32_e32 v30, 0x3fb8aa3b, v30
	v_exp_f32_e32 v30, v30
	v_sub_f32_e32 v33, v33, v224
	v_mul_f32_e32 v33, 0x3fb8aa3b, v33
	v_readlane_b32 s2, v254, 61
	v_add_f32_e32 v32, v30, v36
	v_exp_f32_e32 v36, v33
	v_sub_f32_e32 v33, v34, v224
	v_mul_f32_e32 v33, 0x3fb8aa3b, v33
	v_exp_f32_e32 v37, v33
	v_sub_f32_e32 v33, v35, v224
	v_mul_f32_e32 v33, 0x3fb8aa3b, v33
	v_exp_f32_e32 v38, v33
	v_sub_f32_e32 v33, v46, v224
	v_mul_f32_e32 v33, 0x3fb8aa3b, v33
	v_exp_f32_e32 v39, v33
	v_sub_f32_e32 v33, v44, v224
	v_mul_f32_e32 v33, 0x3fb8aa3b, v33
	v_exp_f32_e32 v40, v33
	v_sub_f32_e32 v33, v47, v224
	v_mul_f32_e32 v33, 0x3fb8aa3b, v33
	v_exp_f32_e32 v43, v33
	v_sub_f32_e32 v33, v48, v224
	v_mul_f32_e32 v33, 0x3fb8aa3b, v33
	v_exp_f32_e32 v44, v33
	v_sub_f32_e32 v33, v49, v224
	v_mul_f32_e32 v33, 0x3fb8aa3b, v33
	v_exp_f32_e32 v41, v33
	v_sub_f32_e32 v33, v50, v224
	v_add_f32_e32 v32, v36, v32
	v_mul_f32_e32 v33, 0x3fb8aa3b, v33
	v_add_f32_e32 v32, v37, v32
	v_exp_f32_e32 v42, v33
	v_sub_f32_e32 v33, v51, v224
	v_add_f32_e32 v32, v38, v32
	v_mul_f32_e32 v33, 0x3fb8aa3b, v33
	v_add_f32_e32 v32, v39, v32
	v_exp_f32_e32 v45, v33
	v_sub_f32_e32 v33, v52, v224
	v_add_f32_e32 v32, v40, v32
	v_mul_f32_e32 v33, 0x3fb8aa3b, v33
	v_add_f32_e32 v32, v43, v32
	v_exp_f32_e32 v46, v33
	v_sub_f32_e32 v33, 0xf149f2ca, v224
	v_add_f32_e32 v32, v44, v32
	v_mul_f32_e32 v33, 0x3fb8aa3b, v33
	v_add_f32_e32 v32, v41, v32
	v_exp_f32_e32 v47, v33
	v_add_f32_e32 v32, v42, v32
	v_add_f32_e32 v32, v45, v32
	v_add_f32_e32 v32, v46, v32
	v_add_f32_e32 v32, v47, v32
	v_add_f32_e32 v32, v47, v32
	v_add_f32_e32 v32, v47, v32
	v_add_f32_e32 v32, v47, v32
	v_add_f32_e32 v32, v47, v32
	v_add_f32_e32 v32, v47, v32
	v_add_f32_e32 v32, v47, v32
	v_add_f32_e32 v32, v47, v32
	v_add_f32_e32 v32, v47, v32
	v_add_f32_e32 v32, v47, v32
	v_add_f32_e32 v32, v47, v32
	v_add_f32_e32 v225, v47, v32
	ds_read2_b32 v[32:33], v197 offset0:80 offset1:81
	v_readlane_b32 s3, v254, 62
	v_cvt_pk_f16_f32 v147, v43, v44
	v_cvt_pk_f16_f32 v146, v39, v40
	v_cvt_pk_f16_f32 v144, v30, v36
	s_waitcnt lgkmcnt(0)
	v_add_f32_e32 v17, v17, v32
	v_cndmask_b32_e64 v32, v209, v17, s[78:79]
	v_add_f32_e32 v17, v18, v33
	ds_read_b32 v18, v197 offset:328
	v_max_f32_e32 v34, 0xf149f2ca, v32
	v_cndmask_b32_e64 v17, v209, v17, s[80:81]
	v_cvt_pk_f16_f32 v137, v45, v46
	v_cvt_pk_f16_f32 v136, v41, v42
	s_waitcnt lgkmcnt(0)
	v_add_f32_e32 v18, v19, v18
	v_cndmask_b32_e64 v18, v209, v18, s[82:83]
	v_max3_f32 v19, v34, v17, v18
	ds_read2_b32 v[34:35], v197 offset0:87 offset1:88
	v_cvt_pk_f16_f32 v138, v47, v47
	v_cvt_pk_f16_f32 v145, v37, v38
	v_mov_b32_e32 v139, v138
	v_mov_b32_e32 v132, v138
	s_waitcnt lgkmcnt(0)
	v_add_f32_e32 v20, v20, v34
	v_cndmask_b32_e64 v33, v209, v20, s[84:85]
	v_add_f32_e32 v20, v21, v35
	v_cndmask_b32_e64 v34, v209, v20, s[86:87]
	ds_read2_b32 v[20:21], v197 offset0:89 offset1:90
	v_max3_f32 v19, v19, v33, v34
	v_cvt_pk_f16_f32 v35, v29, v31
	v_mov_b32_e32 v133, v138
	v_mov_b32_e32 v134, v138
	s_waitcnt lgkmcnt(0)
	v_add_f32_e32 v20, v22, v20
	v_cndmask_b32_e64 v22, v209, v20, s[88:89]
	v_add_f32_e32 v20, v23, v21
	v_cndmask_b32_e64 v23, v209, v20, s[90:91]
	ds_read2_b32 v[20:21], v197 offset0:95 offset1:96
	v_max3_f32 v19, v19, v22, v23
	v_mov_b32_e32 v135, v138
	v_mov_b32_e32 v226, v225
	s_nop 1
	v_permlane32_swap_b32_e32 v225, v226
	s_waitcnt lgkmcnt(0)
	v_add_f32_e32 v0, v0, v20
	v_cndmask_b32_e64 v20, v209, v0, s[92:93]
	v_add_f32_e32 v0, v1, v21
	v_cndmask_b32_e64 v21, v209, v0, s[94:95]
	ds_read2_b32 v[0:1], v197 offset0:97 offset1:98
	v_max3_f32 v19, v19, v20, v21
	s_waitcnt lgkmcnt(0)
; __device__ __forceinline__ void na_item(const Args& a, int layer, int item, LAS unsigned char* lds, int tid, int lane, int wave) {
;     ...
;         for (int nt = 0; nt < 2; ++nt) {
;             const int qc = l31 + 32 * nt; int csq = qc - 8; csq = csq < 0 ? 0 : (csq > 48 ? 48 : csq);
;             const int dlt = 4 * half - csq;
;             const LAS float* bq = bt + (48 + 15 + 4 * half - qc - 32);
;             float m = -3.0e38f;
; #pragma unroll
;             for (int mt = 0; mt < 2; ++mt)
; #pragma unroll
;                 for (int r = 0; r < 16; ++r) { const int kr = (r & 3) + 8 * (r >> 2) + 32 * mt;
;                     const float sv = acc[mt][nt][r] + bq[32 + kr]; const bool ok = (unsigned)(dlt + kr) < 16u; const float sm = ok ? sv : -1.0e30f; acc[mt][nt][r] = sm; m = fmaxf(m, sm); }
;             { const auto sw = __builtin_amdgcn_permlane32_swap(__builtin_bit_cast(unsigned, m), __builtin_bit_cast(unsigned, m), false, false); const unsigned s0 = sw[0], s1 = sw[1]; m = fmaxf(__builtin_bit_cast(float, s0), __builtin_bit_cast(float, s1)); }
;             float l = 0.f;
; #pragma unroll
;             for (int mt = 0; mt < 2; ++mt)
; #pragma unroll
;                 for (int r = 0; r < 16; ++r) { const float p = __expf(acc[mt][nt][r] - m); acc[mt][nt][r] = p; l += p; }
;             { const auto sw = __builtin_amdgcn_permlane32_swap(__builtin_bit_cast(unsigned, l), __builtin_bit_cast(unsigned, l), false, false); const unsigned s0 = sw[0], s1 = sw[1]; l = __builtin_bit_cast(float, s0) + __builtin_bit_cast(float, s1); }
;             mxq[nt] = m; lq[nt] = l;
;         }
;         h16x8 pf[2][2][2];
; #pragma unroll
;         for (int kt = 0; kt < 2; ++kt)
; #pragma unroll
;             for (int nt = 0; nt < 2; ++nt)
; #pragma unroll
;                 for (int sx = 0; sx < 2; ++sx)
; #pragma unroll
;                     for (int e = 0; e < 8; ++e) pf[kt][nt][sx][e] = (h16)acc[kt][nt][8 * sx + e];
;         f32x16 o[2][2];
; #pragma unroll
;         for (int dm = 0; dm < 2; ++dm)
; #pragma unroll
;             for (int nt = 0; nt < 2; ++nt)
; #pragma unroll
;                 for (int r = 0; r < 16; ++r) o[dm][nt][r] = 0.f;
; #pragma unroll
;         for (int dm = 0; dm < 2; ++dm)
; #pragma unroll
;             for (int kt = 0; kt < 2; ++kt)
; #pragma unroll
;                 for (int sx = 0; sx < 2; ++sx) {
;                     h16x8 vf;
	v_add_f32_e32 v0, v2, v0
	v_cndmask_b32_e64 v2, v209, v0, s[96:97]
	v_add_f32_e32 v0, v3, v1
	v_cndmask_b32_e64 v3, v209, v0, s[6:7]
	ds_read2_b32 v[0:1], v197 offset0:103 offset1:104
	v_max3_f32 v19, v19, v2, v3
	s_waitcnt lgkmcnt(0)
	v_add_f32_e32 v0, v4, v0
	v_cndmask_b32_e64 v4, v209, v0, s[12:13]
	v_add_f32_e32 v0, v5, v1
	v_cndmask_b32_e64 v5, v209, v0, s[10:11]
	ds_read2_b32 v[0:1], v197 offset0:105 offset1:106
	v_max3_f32 v19, v19, v4, v5
	s_waitcnt lgkmcnt(0)
	v_add_f32_e32 v0, v6, v0
	v_cndmask_b32_e64 v6, v209, v0, s[14:15]
	v_add_f32_e32 v0, v7, v1
	v_cndmask_b32_e64 v7, v209, v0, s[8:9]
	ds_read2_b32 v[0:1], v197 offset0:111 offset1:112
	v_max3_f32 v19, v19, v6, v7
	s_waitcnt lgkmcnt(0)
	v_add_f32_e32 v0, v8, v0
	v_cndmask_b32_e64 v8, v209, v0, s[50:51]
	v_add_f32_e32 v0, v9, v1
	v_cndmask_b32_e64 v9, v209, v0, s[2:3]
	ds_read2_b32 v[0:1], v197 offset0:113 offset1:114
	v_readlane_b32 s2, v254, 63
	v_readlane_b32 s3, v255, 0
	v_max3_f32 v19, v19, v8, v9
	s_waitcnt lgkmcnt(0)
	v_add_f32_e32 v0, v10, v0
	v_cndmask_b32_e64 v10, v209, v0, s[2:3]
	v_readlane_b32 s2, v255, 1
	v_add_f32_e32 v0, v11, v1
	v_readlane_b32 s3, v255, 2
	s_nop 1
	v_cndmask_b32_e64 v11, v209, v0, s[2:3]
	ds_read2_b32 v[0:1], v197 offset0:119 offset1:120
	v_readlane_b32 s2, v255, 3
	v_readlane_b32 s3, v255, 4
	v_max3_f32 v19, v19, v10, v11
	s_waitcnt lgkmcnt(0)
	v_add_f32_e32 v0, v12, v0
	v_cndmask_b32_e64 v12, v209, v0, s[2:3]
	v_readlane_b32 s2, v255, 5
	v_add_f32_e32 v0, v13, v1
	v_readlane_b32 s3, v255, 6
	s_nop 1
	v_cndmask_b32_e64 v13, v209, v0, s[2:3]
	ds_read2_b32 v[0:1], v197 offset0:121 offset1:122
	v_readlane_b32 s2, v255, 7
	v_readlane_b32 s3, v255, 8
	v_max3_f32 v19, v19, v12, v13
	s_waitcnt lgkmcnt(0)
	v_add_f32_e32 v0, v14, v0
	v_cndmask_b32_e64 v0, v209, v0, s[2:3]
	v_readlane_b32 s2, v255, 9
	v_add_f32_e32 v1, v15, v1
	v_readlane_b32 s3, v255, 10
	s_nop 1
	v_cndmask_b32_e64 v1, v209, v1, s[2:3]
	v_max3_f32 v14, v19, v0, v1
	v_mov_b32_e32 v15, v14
	s_nop 1
	v_permlane32_swap_b32_e32 v14, v15
	v_max_f32_e32 v15, v15, v15
	v_max_f32_e32 v14, v14, v14
	v_max_f32_e32 v162, v14, v15
	v_sub_f32_e32 v14, 0xf149f2ca, v162
	v_mul_f32_e32 v14, 0x3fb8aa3b, v14
	v_exp_f32_e32 v14, v14
	v_sub_f32_e32 v19, v32, v162
	v_mul_f32_e32 v19, 0x3fb8aa3b, v19
	v_sub_f32_e32 v17, v17, v162
	v_add_f32_e32 v15, 0, v14
	v_add_f32_e32 v15, v14, v15
	v_add_f32_e32 v15, v14, v15
	v_add_f32_e32 v15, v14, v15
	v_add_f32_e32 v15, v14, v15
	v_add_f32_e32 v15, v14, v15
	v_exp_f32_e32 v19, v19
	v_mul_f32_e32 v17, 0x3fb8aa3b, v17
	v_sub_f32_e32 v18, v18, v162
	v_sub_f32_e32 v32, v33, v162
	v_add_f32_e32 v15, v14, v15
	v_exp_f32_e32 v17, v17
	v_mul_f32_e32 v18, 0x3fb8aa3b, v18
	v_mul_f32_e32 v32, 0x3fb8aa3b, v32
	v_add_f32_e32 v15, v14, v15
	v_exp_f32_e32 v18, v18
	v_exp_f32_e32 v48, v32
	v_sub_f32_e32 v32, v34, v162
	v_add_f32_e32 v15, v14, v15
	v_mul_f32_e32 v32, 0x3fb8aa3b, v32
	v_sub_f32_e32 v22, v22, v162
	v_add_f32_e32 v15, v19, v15
	v_exp_f32_e32 v49, v32
	v_mul_f32_e32 v22, 0x3fb8aa3b, v22
	v_sub_f32_e32 v23, v23, v162
	v_add_f32_e32 v15, v17, v15
	v_exp_f32_e32 v22, v22
	v_mul_f32_e32 v23, 0x3fb8aa3b, v23
	v_sub_f32_e32 v20, v20, v162
	v_add_f32_e32 v15, v18, v15
	v_exp_f32_e32 v23, v23
	v_mul_f32_e32 v20, 0x3fb8aa3b, v20
	v_sub_f32_e32 v21, v21, v162
	v_add_f32_e32 v15, v48, v15
	v_exp_f32_e32 v20, v20
	v_mul_f32_e32 v21, 0x3fb8aa3b, v21
	v_sub_f32_e32 v2, v2, v162
	v_add_f32_e32 v15, v49, v15
	v_exp_f32_e32 v21, v21
	v_mul_f32_e32 v2, 0x3fb8aa3b, v2
	v_sub_f32_e32 v3, v3, v162
	v_add_f32_e32 v15, v22, v15
	v_exp_f32_e32 v2, v2
	v_mul_f32_e32 v3, 0x3fb8aa3b, v3
	v_sub_f32_e32 v4, v4, v162
	v_add_f32_e32 v15, v23, v15
	v_exp_f32_e32 v3, v3
	v_mul_f32_e32 v4, 0x3fb8aa3b, v4
	v_sub_f32_e32 v5, v5, v162
	v_add_f32_e32 v15, v20, v15
	v_exp_f32_e32 v4, v4
	v_mul_f32_e32 v5, 0x3fb8aa3b, v5
	v_sub_f32_e32 v6, v6, v162
	v_add_f32_e32 v15, v21, v15
	v_exp_f32_e32 v5, v5
	v_mul_f32_e32 v6, 0x3fb8aa3b, v6
	v_sub_f32_e32 v7, v7, v162
	v_add_f32_e32 v15, v2, v15
	v_exp_f32_e32 v6, v6
	v_mul_f32_e32 v7, 0x3fb8aa3b, v7
	v_sub_f32_e32 v8, v8, v162
	v_add_f32_e32 v15, v3, v15
	v_exp_f32_e32 v7, v7
	v_mul_f32_e32 v8, 0x3fb8aa3b, v8
	v_sub_f32_e32 v9, v9, v162
	v_add_f32_e32 v15, v4, v15
	v_exp_f32_e32 v8, v8
	v_mul_f32_e32 v9, 0x3fb8aa3b, v9
	v_sub_f32_e32 v10, v10, v162
	v_add_f32_e32 v15, v5, v15
	v_exp_f32_e32 v9, v9
	v_mul_f32_e32 v10, 0x3fb8aa3b, v10
	v_sub_f32_e32 v11, v11, v162
	v_add_f32_e32 v15, v6, v15
	v_exp_f32_e32 v10, v10
	v_mul_f32_e32 v11, 0x3fb8aa3b, v11
	v_sub_f32_e32 v12, v12, v162
	v_add_f32_e32 v15, v7, v15
	v_exp_f32_e32 v11, v11
	v_mul_f32_e32 v12, 0x3fb8aa3b, v12
	v_sub_f32_e32 v13, v13, v162
	v_add_f32_e32 v15, v8, v15
	v_exp_f32_e32 v12, v12
	v_mul_f32_e32 v13, 0x3fb8aa3b, v13
	v_sub_f32_e32 v0, v0, v162
	v_add_f32_e32 v15, v9, v15
	v_exp_f32_e32 v13, v13
	v_mul_f32_e32 v0, 0x3fb8aa3b, v0
	v_sub_f32_e32 v1, v1, v162
	v_add_f32_e32 v15, v10, v15
	v_exp_f32_e32 v0, v0
	v_mul_f32_e32 v1, 0x3fb8aa3b, v1
	v_add_f32_e32 v15, v11, v15
	v_exp_f32_e32 v1, v1
	v_add_f32_e32 v15, v12, v15
	v_add_f32_e32 v15, v13, v15
	v_add_f32_e32 v15, v0, v15
	v_add_f32_e32 v163, v1, v15
	v_cvt_pk_f16_f32 v143, v6, v7
	v_cvt_pk_f16_f32 v142, v4, v5
	v_cvt_pk_f16_f32 v141, v2, v3
	v_cvt_pk_f16_f32 v131, v0, v1
	ds_read_u16 v0, v198
	ds_read_u16 v4, v198 offset:144
	ds_read_u16 v1, v198 offset:288
	ds_read_u16 v5, v198 offset:432
	ds_read_u16 v2, v198 offset:1152
	ds_read_u16 v6, v198 offset:1296
	ds_read_u16 v3, v198 offset:1440
	ds_read_u16 v7, v198 offset:1584
	s_mov_b32 s2, 0x5040100
	s_waitcnt lgkmcnt(4)
	v_perm_b32 v1, v5, v1, s2
	s_waitcnt lgkmcnt(2)
; #define LAS __attribute__((address_space(3)))
; __device__ __forceinline__ void na_item(const Args& a, int layer, int item, LAS unsigned char* lds, int tid, int lane, int wave) {
;     ...
;         f32x16 o[2][2];
; #pragma unroll
;         for (int dm = 0; dm < 2; ++dm)
; #pragma unroll
;             for (int nt = 0; nt < 2; ++nt)
; #pragma unroll
;                 for (int r = 0; r < 16; ++r) o[dm][nt][r] = 0.f;
; #pragma unroll
;         for (int dm = 0; dm < 2; ++dm)
; #pragma unroll
;             for (int kt = 0; kt < 2; ++kt)
; #pragma unroll
;                 for (int sx = 0; sx < 2; ++sx) {
;                     h16x8 vf;
;                     const LAS unsigned char* vb = lds + NA_VOFF + (aw * 64 + 32 * kt + 16 * sx + 4 * half) * NA_PITCH + (l31 + 32 * dm) * 2;
; #pragma unroll
;                     for (int e = 0; e < 8; ++e) vf[e] = *(const LAS h16*)(vb + ((e & 3) + 8 * (e >> 2)) * NA_PITCH);
;                     o[dm][0] = __builtin_amdgcn_mfma_f32_32x32x16_f16(vf, pf[kt][0][sx], o[dm][0], 0, 0, 0);
;                     o[dm][1] = __builtin_amdgcn_mfma_f32_32x32x16_f16(vf, pf[kt][1][sx], o[dm][1], 0, 0, 0);
;                 }
	v_perm_b32 v2, v6, v2, s2
	v_perm_b32 v0, v4, v0, s2
	s_waitcnt lgkmcnt(0)
	v_perm_b32 v3, v7, v3, s2
	v_cvt_pk_f16_f32 v36, v14, v14
	ds_read_u16 v40, v198 offset:2304
	ds_read_u16 v44, v198 offset:2448
	ds_read_u16 v41, v198 offset:2592
	ds_read_u16 v45, v198 offset:2736
	ds_read_u16 v42, v198 offset:3456
	ds_read_u16 v46, v198 offset:3600
	ds_read_u16 v43, v198 offset:3744
	ds_read_u16 v47, v198 offset:3888
	v_cvt_pk_f16_f32 v34, v27, v28
	v_cvt_pk_f16_f32 v33, v25, v26
	v_cvt_pk_f16_f32 v32, v16, v24
	v_mov_b32_e32 v37, v36
	v_mov_b32_e32 v38, v36
	v_mov_b32_e32 v39, v36
	v_cvt_pk_f16_f32 v148, v14, v19
	v_cvt_pk_f16_f32 v149, v17, v18
	v_cvt_pk_f16_f32 v151, v22, v23
	v_cvt_pk_f16_f32 v140, v20, v21
	v_cvt_pk_f16_f32 v130, v12, v13
	v_cvt_pk_f16_f32 v129, v10, v11
	v_cvt_pk_f16_f32 v128, v8, v9
	v_mfma_f32_32x32x16_f16 v[16:31], v[0:3], v[32:35], 0
	s_waitcnt lgkmcnt(0)
	v_perm_b32 v43, v47, v43, s2
	v_perm_b32 v42, v46, v42, s2
	v_perm_b32 v41, v45, v41, s2
	v_perm_b32 v40, v44, v40, s2
	v_cvt_pk_f16_f32 v150, v48, v49
	v_mov_b32_e32 v204, v163
	s_nop 1
	v_permlane32_swap_b32_e32 v163, v204
	v_mfma_f32_32x32x16_f16 v[0:15], v[0:3], v[36:39], 0
	v_mfma_f32_32x32x16_f16 v[16:31], v[40:43], v[144:147], v[16:31]
	v_mfma_f32_32x32x16_f16 v[0:15], v[40:43], v[148:151], v[0:15]
	ds_read_u16 v40, v198 offset:4608
	ds_read_u16 v44, v198 offset:4752
	ds_read_u16 v41, v198 offset:4896
	ds_read_u16 v45, v198 offset:5040
	ds_read_u16 v42, v198 offset:5760
	ds_read_u16 v46, v198 offset:5904
	ds_read_u16 v43, v198 offset:6048
	ds_read_u16 v47, v198 offset:6192
	s_waitcnt lgkmcnt(4)
	v_perm_b32 v41, v45, v41, s2
	v_perm_b32 v40, v44, v40, s2
	s_waitcnt lgkmcnt(2)
	v_perm_b32 v42, v46, v42, s2
	s_waitcnt lgkmcnt(0)
	v_perm_b32 v43, v47, v43, s2
	s_nop 1
	v_mfma_f32_32x32x16_f16 v[16:31], v[40:43], v[136:139], v[16:31]
	v_mfma_f32_32x32x16_f16 v[0:15], v[40:43], v[140:143], v[0:15]
	ds_read_u16 v40, v198 offset:6912
	ds_read_u16 v44, v198 offset:7056
	ds_read_u16 v41, v198 offset:7200
	ds_read_u16 v45, v198 offset:7344
	ds_read_u16 v42, v198 offset:8064
	ds_read_u16 v46, v198 offset:8208
	ds_read_u16 v43, v198 offset:8352
	ds_read_u16 v47, v198 offset:8496
	s_waitcnt lgkmcnt(4)
	v_perm_b32 v41, v45, v41, s2
	v_perm_b32 v40, v44, v40, s2
	s_waitcnt lgkmcnt(2)
	v_perm_b32 v42, v46, v42, s2
	s_waitcnt lgkmcnt(0)
	v_perm_b32 v43, v47, v43, s2
	s_nop 1
	v_mfma_f32_32x32x16_f16 v[16:31], v[40:43], v[132:135], v[16:31]
	v_mfma_f32_32x32x16_f16 v[0:15], v[40:43], v[128:131], v[0:15]
	ds_read_u16 v40, v198 offset:64
	ds_read_u16 v44, v198 offset:208
	ds_read_u16 v41, v198 offset:352
	ds_read_u16 v45, v198 offset:496
	ds_read_u16 v42, v198 offset:1216
	ds_read_u16 v46, v198 offset:1360
	ds_read_u16 v43, v198 offset:1504
	ds_read_u16 v47, v198 offset:1648
	s_waitcnt lgkmcnt(4)
	v_perm_b32 v41, v45, v41, s2
	v_perm_b32 v40, v44, v40, s2
	s_waitcnt lgkmcnt(2)
	v_perm_b32 v42, v46, v42, s2
	ds_read_u16 v154, v198 offset:2368
	ds_read_u16 v164, v198 offset:2512
	ds_read_u16 v155, v198 offset:2656
	ds_read_u16 v165, v198 offset:2800
	ds_read_u16 v156, v198 offset:3520
	ds_read_u16 v166, v198 offset:3664
	ds_read_u16 v157, v198 offset:3808
	ds_read_u16 v167, v198 offset:3952
	s_waitcnt lgkmcnt(8)
	v_perm_b32 v43, v47, v43, s2
	s_waitcnt lgkmcnt(4)
	v_perm_b32 v155, v165, v155, s2
	s_waitcnt lgkmcnt(2)
	v_perm_b32 v156, v166, v156, s2
	v_mfma_f32_32x32x16_f16 v[48:63], v[40:43], v[32:35], 0
	s_waitcnt lgkmcnt(0)
	v_perm_b32 v157, v167, v157, s2
	v_perm_b32 v154, v164, v154, s2
	v_mfma_f32_32x32x16_f16 v[32:47], v[40:43], v[36:39], 0
	s_nop 0
	v_mfma_f32_32x32x16_f16 v[48:63], v[154:157], v[144:147], v[48:63]
	v_mfma_f32_32x32x16_f16 v[32:47], v[154:157], v[148:151], v[32:47]
	ds_read_u16 v144, v198 offset:4672
	ds_read_u16 v148, v198 offset:4816
	ds_read_u16 v145, v198 offset:4960
	ds_read_u16 v149, v198 offset:5104
	ds_read_u16 v146, v198 offset:5824
	ds_read_u16 v150, v198 offset:5968
	ds_read_u16 v147, v198 offset:6112
	ds_read_u16 v151, v198 offset:6256
	s_waitcnt lgkmcnt(4)
	v_perm_b32 v145, v149, v145, s2
	v_perm_b32 v144, v148, v144, s2
	s_waitcnt lgkmcnt(2)
	v_perm_b32 v146, v150, v146, s2
	s_waitcnt lgkmcnt(0)
	v_perm_b32 v147, v151, v147, s2
	s_nop 1
	v_mfma_f32_32x32x16_f16 v[48:63], v[144:147], v[136:139], v[48:63]
	v_mfma_f32_32x32x16_f16 v[32:47], v[144:147], v[140:143], v[32:47]
	ds_read_u16 v136, v198 offset:6976
	ds_read_u16 v140, v198 offset:7120
	ds_read_u16 v137, v198 offset:7264
	ds_read_u16 v141, v198 offset:7408
	ds_read_u16 v138, v198 offset:8128
	ds_read_u16 v142, v198 offset:8272
	ds_read_u16 v139, v198 offset:8416
	ds_read_u16 v143, v198 offset:8560
	s_waitcnt lgkmcnt(4)
	v_perm_b32 v137, v141, v137, s2
	v_perm_b32 v136, v140, v136, s2
	s_waitcnt lgkmcnt(2)
	v_perm_b32 v138, v142, v138, s2
	s_waitcnt lgkmcnt(0)
	v_perm_b32 v139, v143, v139, s2
	s_barrier
; #define LAS __attribute__((address_space(3)))
; __device__ __forceinline__ void na_item(const Args& a, int layer, int item, LAS unsigned char* lds, int tid, int lane, int wave) {
;     ...
;                     o[dm][0] = __builtin_amdgcn_mfma_f32_32x32x16_f16(vf, pf[kt][0][sx], o[dm][0], 0, 0, 0);
;                     o[dm][1] = __builtin_amdgcn_mfma_f32_32x32x16_f16(vf, pf[kt][1][sx], o[dm][1], 0, 0, 0);
;                 }
;         __syncthreads();
; #pragma unroll
;         for (int nt = 0; nt < 2; ++nt) {
;             LAS float* part = (LAS float*)lds + (size_t)(aw * 64 + l31 + 32 * nt) * NA_PP;
; #pragma unroll
;             for (int dm = 0; dm < 2; ++dm)
; #pragma unroll
;                 for (int r = 0; r < 16; ++r) part[(r & 3) + 8 * (r >> 2) + 4 * half + 32 * dm] = o[dm][nt][r];
;             if (half == 0) { part[64] = mxq[nt]; part[65] = lq[nt]; }
;         }
	s_nop 0
	v_mfma_f32_32x32x16_f16 v[32:47], v[136:139], v[128:131], v[32:47]
	v_add_u32_e32 v128, v211, v194
	v_mfma_f32_32x32x16_f16 v[48:63], v[136:139], v[132:135], v[48:63]
	ds_write2_b32 v128, v16, v17 offset1:1
	ds_write2_b32 v128, v18, v19 offset0:2 offset1:3
	ds_write2_b32 v128, v20, v21 offset0:8 offset1:9
	ds_write2_b32 v128, v22, v23 offset0:10 offset1:11
	ds_write2_b32 v128, v24, v25 offset0:16 offset1:17
	ds_write2_b32 v128, v26, v27 offset0:18 offset1:19
	ds_write2_b32 v128, v28, v29 offset0:24 offset1:25
	ds_write2_b32 v128, v30, v31 offset0:26 offset1:27
	s_nop 3
	ds_write2_b32 v128, v48, v49 offset0:32 offset1:33
	ds_write2_b32 v128, v50, v51 offset0:34 offset1:35
	ds_write2_b32 v128, v52, v53 offset0:40 offset1:41
	ds_write2_b32 v128, v54, v55 offset0:42 offset1:43
	ds_write2_b32 v128, v56, v57 offset0:48 offset1:49
	ds_write2_b32 v128, v58, v59 offset0:50 offset1:51
	ds_write2_b32 v128, v60, v61 offset0:56 offset1:57
	ds_write2_b32 v128, v62, v63 offset0:58 offset1:59
	s_and_saveexec_b64 s[2:3], s[18:19]
	v_add_f32_e32 v16, v225, v226
	ds_write2_b32 v211, v224, v16 offset0:64 offset1:65
	s_or_b64 exec, exec, s[2:3]
	v_add_u32_e32 v16, v212, v194
	ds_write2_b32 v16, v0, v1 offset1:1
	ds_write2_b32 v16, v2, v3 offset0:2 offset1:3
	ds_write2_b32 v16, v4, v5 offset0:8 offset1:9
	ds_write2_b32 v16, v6, v7 offset0:10 offset1:11
	ds_write2_b32 v16, v8, v9 offset0:16 offset1:17
	ds_write2_b32 v16, v10, v11 offset0:18 offset1:19
	ds_write2_b32 v16, v12, v13 offset0:24 offset1:25
	ds_write2_b32 v16, v14, v15 offset0:26 offset1:27
	ds_write2_b32 v16, v32, v33 offset0:32 offset1:33
	ds_write2_b32 v16, v34, v35 offset0:34 offset1:35
	ds_write2_b32 v16, v36, v37 offset0:40 offset1:41
	ds_write2_b32 v16, v38, v39 offset0:42 offset1:43
	ds_write2_b32 v16, v40, v41 offset0:48 offset1:49
	ds_write2_b32 v16, v42, v43 offset0:50 offset1:51
	ds_write2_b32 v16, v44, v45 offset0:56 offset1:57
	ds_write2_b32 v16, v46, v47 offset0:58 offset1:59
	s_mov_b64 s[2:3], exec
	v_mov_b64_e32 v[154:155], v[158:159]
	s_and_b64 s[16:17], s[2:3], s[18:19]
	v_mov_b64_e32 v[156:157], v[160:161]
	s_mov_b64 exec, s[16:17]
	s_cbranch_execz .LBB0_456
	v_add_f32_e32 v0, v163, v204
	ds_write2_b32 v212, v162, v0 offset0:64 offset1:65
	s_branch .LBB0_456
